# P0 reads x once: non-temporal loads keep H and the transposed w_in (written by P0, read by P1) in the memory-side cache
# speedup vs baseline: 1.0155x; 1.0107x over previous
; __global__ void __launch_bounds__(NWAVES * 64, 2) hybrid_fwd(Args args) {
;     ...
;         f32x4 wmix[8];
; #pragma unroll
;         for (int j = 0; j < 8; ++j) wmix[j] = ((const f32x4*)norm_mix_w + lane)[64 * j];
;         for (int m0 = gw * 4; m0 < M; m0 += NGW * 4) {
;             f32x4 v[4][8]; float s[4] = {0.f, 0.f, 0.f, 0.f};
; #pragma unroll
;             for (int q = 0; q < 4; ++q) { const f32x4* xr = (const f32x4*)(x + (size_t)(m0 + q) * DM) + lane;
; #pragma unroll
;                 for (int j = 0; j < 8; ++j) v[q][j] = xr[64 * j]; }
.LBB0_23:
	v_readlane_b32 s64, v244, 28
	s_cmpk_lt_i32 s64, 0x1000
	s_movk_i32 s18, 0x1000
	s_cbranch_scc0 .LBB0_26
	v_readlane_b32 s36, v244, 12
	v_lshlrev_b32_e32 v32, 4, v184
	v_mov_b32_e32 v33, 0
	v_readlane_b32 s38, v244, 14
	v_readlane_b32 s39, v244, 15
	s_lshl_b32 s8, s64, 2
	v_readlane_b32 s0, v244, 4
	v_lshl_add_u64 v[0:1], s[38:39], 0, v[32:33]
	v_add_co_u32_e32 v34, vcc, 0x1000, v0
	v_readlane_b32 s1, v244, 5
	s_nop 0
	v_addc_co_u32_e32 v35, vcc, 0, v1, vcc
	global_load_dwordx4 v[0:3], v[34:35], off offset:3072 nt
	global_load_dwordx4 v[4:7], v[34:35], off offset:2048 nt
	global_load_dwordx4 v[8:11], v[34:35], off offset:1024 nt
	global_load_dwordx4 v[12:15], v[34:35], off nt
	global_load_dwordx4 v[16:19], v32, s[38:39] offset:3072 nt
	global_load_dwordx4 v[20:23], v32, s[38:39] offset:2048 nt
	global_load_dwordx4 v[24:27], v32, s[38:39] offset:1024 nt
	global_load_dwordx4 v[28:31], v32, s[38:39] nt
	v_mbcnt_lo_u32_b32 v34, -1, 0
	v_mbcnt_hi_u32_b32 v34, -1, v34
	v_and_b32_e32 v35, 64, v34
	v_add_u32_e32 v35, 64, v35
	v_xor_b32_e32 v36, 1, v34
	v_cmp_lt_i32_e32 vcc, v36, v35
	s_ashr_i32 s9, s8, 31
	s_lshl_b32 s12, s0, 5
	v_cndmask_b32_e32 v36, v34, v36, vcc
	v_lshlrev_b32_e32 v170, 2, v36
	v_xor_b32_e32 v36, 2, v34
	v_cmp_lt_i32_e32 vcc, v36, v35
	s_lshl_b64 s[0:1], s[8:9], 12
	s_add_u32 s0, s76, s0
	v_cndmask_b32_e32 v36, v34, v36, vcc
	v_lshlrev_b32_e32 v171, 2, v36
	v_xor_b32_e32 v36, 4, v34
	v_cmp_lt_i32_e32 vcc, v36, v35
	s_addc_u32 s1, s77, s1
	s_ashr_i32 s13, s12, 31
	v_cndmask_b32_e32 v36, v34, v36, vcc
	v_lshlrev_b32_e32 v172, 2, v36
	v_xor_b32_e32 v36, 8, v34
	v_cmp_lt_i32_e32 vcc, v36, v35
	s_lshl_b64 s[14:15], s[12:13], 12
	v_readlane_b32 s37, v244, 13
	v_cndmask_b32_e32 v36, v34, v36, vcc
	v_lshlrev_b32_e32 v173, 2, v36
	v_xor_b32_e32 v36, 16, v34
	v_cmp_lt_i32_e32 vcc, v36, v35
	v_mov_b32_e32 v176, 0x358637bd
	v_readlane_b32 s40, v244, 16
	v_cndmask_b32_e32 v36, v34, v36, vcc
	v_lshlrev_b32_e32 v174, 2, v36
	v_xor_b32_e32 v36, 32, v34
	v_cmp_lt_i32_e32 vcc, v36, v35
	v_mov_b32_e32 v35, v33
	v_readlane_b32 s41, v244, 17
	v_cndmask_b32_e32 v34, v34, v36, vcc
	v_lshlrev_b32_e32 v175, 2, v34
	v_lshlrev_b32_e32 v34, 3, v184
	v_lshl_add_u64 v[34:35], s[0:1], 0, v[34:35]
	s_mov_b64 s[0:1], 0x6800000
	v_lshl_add_u64 v[160:161], v[34:35], 0, s[0:1]
	s_lshl_b64 s[0:1], s[8:9], 13
	s_add_u32 s0, s36, s0
	s_addc_u32 s1, s37, s1
	v_lshl_add_u64 v[162:163], s[0:1], 0, v[32:33]
	s_lshl_b64 s[16:17], s[12:13], 13
	s_movk_i32 s9, 0x2000
	s_movk_i32 s13, 0x3000
	v_readlane_b32 s42, v244, 18
	v_readlane_b32 s43, v244, 19
	v_readlane_b32 s44, v244, 20
	v_readlane_b32 s45, v244, 21
	v_readlane_b32 s46, v244, 22
	v_readlane_b32 s47, v244, 23
	v_readlane_b32 s48, v244, 24
	v_readlane_b32 s49, v244, 25
	v_readlane_b32 s50, v244, 26
	v_readlane_b32 s51, v244, 27
.LBB0_25:
	v_add_co_u32_e32 v48, vcc, 0x1000, v162
	s_mov_b64 s[0:1], vcc
	v_add_co_u32_e32 v166, vcc, s9, v160
	global_load_dwordx4 v[44:47], v[162:163], off nt
	global_load_dwordx4 v[40:43], v[162:163], off offset:1024 nt
	global_load_dwordx4 v[36:39], v[162:163], off offset:2048 nt
	global_load_dwordx4 v[32:35], v[162:163], off offset:3072 nt
	v_addc_co_u32_e32 v167, vcc, 0, v161, vcc
	v_add_co_u32_e32 v168, vcc, s18, v160
	s_add_i32 s8, s8, s12
	s_nop 0
	v_addc_co_u32_e32 v169, vcc, 0, v161, vcc
	v_add_co_u32_e32 v164, vcc, s13, v160
	s_cmpk_lt_i32 s8, 0x4000
	s_nop 0
	v_addc_co_u32_e32 v165, vcc, 0, v161, vcc
	v_add_co_u32_e32 v50, vcc, 0x2000, v162
	s_mov_b64 s[4:5], vcc
	v_addc_co_u32_e64 v49, vcc, 0, v163, s[0:1]
	global_load_dwordx4 v[156:159], v[48:49], off nt
	global_load_dwordx4 v[152:155], v[48:49], off offset:1024 nt
	global_load_dwordx4 v[148:151], v[48:49], off offset:2048 nt
	global_load_dwordx4 v[144:147], v[48:49], off offset:3072 nt
	v_add_co_u32_e32 v48, vcc, 0x3000, v162
	s_mov_b64 s[0:1], vcc
	v_addc_co_u32_e64 v51, vcc, 0, v163, s[4:5]
	v_add_co_u32_e32 v52, vcc, 0x4000, v162
	s_mov_b64 s[4:5], vcc
	global_load_dwordx4 v[140:143], v[50:51], off nt
	global_load_dwordx4 v[136:139], v[50:51], off offset:1024 nt
	global_load_dwordx4 v[132:135], v[50:51], off offset:2048 nt
	global_load_dwordx4 v[124:127], v[50:51], off offset:3072 nt
	v_addc_co_u32_e64 v49, vcc, 0, v163, s[0:1]
	v_add_co_u32_e32 v50, vcc, 0x5000, v162
	s_mov_b64 s[0:1], vcc
	v_addc_co_u32_e64 v53, vcc, 0, v163, s[4:5]
	global_load_dwordx4 v[128:131], v[48:49], off nt
	global_load_dwordx4 v[120:123], v[48:49], off offset:1024 nt
	global_load_dwordx4 v[116:119], v[48:49], off offset:2048 nt
	global_load_dwordx4 v[112:115], v[48:49], off offset:3072 nt
	global_load_dwordx4 v[108:111], v[52:53], off nt
	global_load_dwordx4 v[104:107], v[52:53], off offset:1024 nt
	global_load_dwordx4 v[100:103], v[52:53], off offset:2048 nt
	global_load_dwordx4 v[96:99], v[52:53], off offset:3072 nt
	v_add_co_u32_e32 v48, vcc, 0x6000, v162
	v_addc_co_u32_e64 v51, s[0:1], 0, v163, s[0:1]
	s_nop 0
	v_addc_co_u32_e32 v49, vcc, 0, v163, vcc
	global_load_dwordx4 v[92:95], v[50:51], off nt
	global_load_dwordx4 v[88:91], v[50:51], off offset:1024 nt
	global_load_dwordx4 v[84:87], v[50:51], off offset:2048 nt
	global_load_dwordx4 v[80:83], v[50:51], off offset:3072 nt
	global_load_dwordx4 v[76:79], v[48:49], off nt
	global_load_dwordx4 v[72:75], v[48:49], off offset:1024 nt
	global_load_dwordx4 v[68:71], v[48:49], off offset:2048 nt
	global_load_dwordx4 v[60:63], v[48:49], off offset:3072 nt
	v_add_co_u32_e32 v50, vcc, 0x7000, v162
	s_waitcnt vmcnt(27)
; __global__ void __launch_bounds__(NWAVES * 64, 2) hybrid_fwd(Args args) {
;     ...
;             for (int q = 0; q < 4; ++q) { const f32x4* xr = (const f32x4*)(x + (size_t)(m0 + q) * DM) + lane;
; #pragma unroll
;                 for (int j = 0; j < 8; ++j) v[q][j] = xr[64 * j]; }
; #pragma unroll
;             for (int q = 0; q < 4; ++q)
; #pragma unroll
;                 for (int j = 0; j < 8; ++j) s[q] += (v[q][j].x * v[q][j].x + v[q][j].y * v[q][j].y) + (v[q][j].z * v[q][j].z + v[q][j].w * v[q][j].w);
	v_mul_f32_e32 v177, v45, v45
	v_addc_co_u32_e32 v51, vcc, 0, v163, vcc
	global_load_dwordx4 v[64:67], v[50:51], off nt
	global_load_dwordx4 v[56:59], v[50:51], off offset:1024 nt
	global_load_dwordx4 v[52:55], v[50:51], off offset:2048 nt
	s_nop 0
	global_load_dwordx4 v[48:51], v[50:51], off offset:3072 nt
	v_mul_f32_e32 v178, v47, v47
	s_waitcnt vmcnt(30)
	v_mul_f32_e32 v179, v41, v41
	v_mul_f32_e32 v180, v43, v43
	s_waitcnt vmcnt(29)
	v_mul_f32_e32 v181, v37, v37
	v_mul_f32_e32 v182, v39, v39
	v_fmac_f32_e32 v177, v44, v44
	v_fmac_f32_e32 v178, v46, v46
	v_fmac_f32_e32 v179, v40, v40
	v_fmac_f32_e32 v180, v42, v42
	s_waitcnt vmcnt(28)
	v_mul_f32_e32 v183, v33, v33
	v_mul_f32_e32 v186, v35, v35
	v_fmac_f32_e32 v181, v36, v36
	v_fmac_f32_e32 v182, v38, v38
	v_add_f32_e32 v177, v177, v178
	v_add_f32_e32 v178, v179, v180
	v_fmac_f32_e32 v183, v32, v32
	v_fmac_f32_e32 v186, v34, v34
	v_add_f32_e32 v179, v181, v182
	s_waitcnt vmcnt(27)
	v_mul_f32_e32 v181, v157, v157
	v_mul_f32_e32 v182, v159, v159
	v_add_f32_e32 v177, v177, v178
	v_add_f32_e32 v180, v183, v186
	s_waitcnt vmcnt(26)
	v_mul_f32_e32 v183, v153, v153
	s_waitcnt vmcnt(23)
	v_mul_f32_e32 v178, v141, v141
	v_mul_f32_e32 v191, v143, v143
	s_waitcnt vmcnt(22)
	v_mul_f32_e32 v192, v137, v137
	v_mul_f32_e32 v193, v139, v139
	s_waitcnt vmcnt(21)
	v_mul_f32_e32 v194, v133, v133
	v_mul_f32_e32 v195, v135, v135
	s_waitcnt vmcnt(20)
	v_mul_f32_e32 v196, v125, v125
	v_mul_f32_e32 v197, v127, v127
	v_mul_f32_e32 v186, v155, v155
	v_mul_f32_e32 v187, v149, v149
	v_mul_f32_e32 v188, v151, v151
	v_fmac_f32_e32 v181, v156, v156
	v_fmac_f32_e32 v182, v158, v158
	v_add_f32_e32 v177, v177, v179
	v_fmac_f32_e32 v178, v140, v140
	v_fmac_f32_e32 v191, v142, v142
	v_fmac_f32_e32 v192, v136, v136
	v_fmac_f32_e32 v193, v138, v138
	v_fmac_f32_e32 v194, v132, v132
	v_fmac_f32_e32 v195, v134, v134
	v_fmac_f32_e32 v196, v124, v124
	v_fmac_f32_e32 v197, v126, v126
	v_mul_f32_e32 v189, v145, v145
	v_mul_f32_e32 v190, v147, v147
	v_fmac_f32_e32 v183, v152, v152
	v_fmac_f32_e32 v186, v154, v154
	v_fmac_f32_e32 v187, v148, v148
	v_fmac_f32_e32 v188, v150, v150
	v_add_f32_e32 v179, v181, v182
	v_add_f32_e32 v177, v177, v180
	v_add_f32_e32 v178, v178, v191
	v_add_f32_e32 v180, v192, v193
	v_add_f32_e32 v191, v194, v195
	v_add_f32_e32 v192, v196, v197
	s_waitcnt vmcnt(15)
	v_mul_f32_e32 v193, v109, v109
	v_mul_f32_e32 v194, v111, v111
	s_waitcnt vmcnt(14)
	v_mul_f32_e32 v195, v105, v105
	v_mul_f32_e32 v196, v107, v107
	s_waitcnt vmcnt(13)
	v_mul_f32_e32 v197, v101, v101
	v_mul_f32_e32 v201, v103, v103
	v_fmac_f32_e32 v189, v144, v144
	v_fmac_f32_e32 v190, v146, v146
	v_add_f32_e32 v181, v183, v186
	v_add_f32_e32 v182, v187, v188
	v_mul_f32_e32 v186, v129, v129
	v_mul_f32_e32 v187, v131, v131
	s_waitcnt vmcnt(12)
	v_mul_f32_e32 v202, v97, v97
	v_mul_f32_e32 v203, v99, v99
	v_add_f32_e32 v177, v177, v179
	v_add_f32_e32 v178, v178, v180
	v_fmac_f32_e32 v193, v108, v108
	v_fmac_f32_e32 v194, v110, v110
	v_fmac_f32_e32 v195, v104, v104
	v_fmac_f32_e32 v196, v106, v106
	v_fmac_f32_e32 v197, v100, v100
	v_fmac_f32_e32 v201, v102, v102
	v_add_f32_e32 v183, v189, v190
	v_mul_f32_e32 v188, v121, v121
	v_mul_f32_e32 v189, v123, v123
	v_mul_f32_e32 v190, v117, v117
	v_mul_f32_e32 v198, v119, v119
	v_mul_f32_e32 v199, v113, v113
	v_mul_f32_e32 v200, v115, v115
	v_fmac_f32_e32 v186, v128, v128
	v_fmac_f32_e32 v187, v130, v130
	v_fmac_f32_e32 v202, v96, v96
	v_fmac_f32_e32 v203, v98, v98
	v_add_f32_e32 v177, v177, v181
	v_add_f32_e32 v178, v178, v191
	v_add_f32_e32 v181, v193, v194
	v_add_f32_e32 v191, v195, v196
	v_add_f32_e32 v193, v197, v201
	s_waitcnt vmcnt(7)
	v_mul_f32_e32 v195, v77, v77
	v_mul_f32_e32 v196, v79, v79
	s_waitcnt vmcnt(6)
	v_mul_f32_e32 v197, v73, v73
	v_mul_f32_e32 v201, v75, v75
	v_fmac_f32_e32 v188, v120, v120
	v_fmac_f32_e32 v189, v122, v122
	v_fmac_f32_e32 v190, v116, v116
	v_fmac_f32_e32 v198, v118, v118
	v_fmac_f32_e32 v199, v112, v112
	v_fmac_f32_e32 v200, v114, v114
	v_add_f32_e32 v179, v186, v187
	v_add_f32_e32 v194, v202, v203
	s_waitcnt vmcnt(5)
	v_mul_f32_e32 v202, v69, v69
	v_mul_f32_e32 v203, v71, v71
	v_add_f32_e32 v177, v177, v182
	v_add_f32_e32 v178, v178, v192
	v_add_f32_e32 v181, v181, v191
	v_fmac_f32_e32 v195, v76, v76
	v_fmac_f32_e32 v196, v78, v78
	v_fmac_f32_e32 v197, v72, v72
	v_fmac_f32_e32 v201, v74, v74
	v_add_f32_e32 v180, v188, v189
	v_add_f32_e32 v186, v190, v198
	v_add_f32_e32 v187, v199, v200
	v_mul_f32_e32 v188, v93, v93
	v_mul_f32_e32 v189, v95, v95
	v_mul_f32_e32 v190, v89, v89
	v_mul_f32_e32 v198, v91, v91
	v_mul_f32_e32 v199, v85, v85
	v_mul_f32_e32 v200, v87, v87
	s_waitcnt vmcnt(4)
	v_mul_f32_e32 v206, v61, v61
	v_mul_f32_e32 v207, v63, v63
	v_fmac_f32_e32 v202, v68, v68
	v_fmac_f32_e32 v203, v70, v70
	v_add_f32_e32 v177, v177, v183
	v_add_f32_e32 v178, v178, v179
	v_add_f32_e32 v179, v181, v193
	v_add_f32_e32 v181, v195, v196
	v_add_f32_e32 v183, v197, v201
	v_mul_f32_e32 v204, v81, v81
	v_mul_f32_e32 v205, v83, v83
	v_fmac_f32_e32 v188, v92, v92
	v_fmac_f32_e32 v189, v94, v94
	v_fmac_f32_e32 v190, v88, v88
	v_fmac_f32_e32 v198, v90, v90
	v_fmac_f32_e32 v199, v84, v84
	v_fmac_f32_e32 v200, v86, v86
	v_fmac_f32_e32 v206, v60, v60
	v_fmac_f32_e32 v207, v62, v62
	s_waitcnt vmcnt(3)
	v_mul_f32_e32 v191, v65, v65
	v_mul_f32_e32 v192, v67, v67
	v_add_f32_e32 v193, v202, v203
	ds_bpermute_b32 v196, v170, v177
	v_add_f32_e32 v178, v178, v180
	v_add_f32_e32 v180, v181, v183
	v_fmac_f32_e32 v204, v80, v80
	v_fmac_f32_e32 v205, v82, v82
	v_add_f32_e32 v182, v188, v189
	v_add_f32_e32 v188, v190, v198
	v_add_f32_e32 v189, v199, v200
	s_waitcnt vmcnt(2)
; __device__ __forceinline__ float wave_sum(float v) {
; #pragma unroll
;     for (int o = 1; o < 64; o <<= 1) v += __shfl_xor(v, o);
;     return v;
; __global__ void __launch_bounds__(NWAVES * 64, 2) hybrid_fwd(Args args) {
;     ...
;                 for (int j = 0; j < 8; ++j) s[q] += (v[q][j].x * v[q][j].x + v[q][j].y * v[q][j].y) + (v[q][j].z * v[q][j].z + v[q][j].w * v[q][j].w);
; #pragma unroll
;             for (int q = 0; q < 4; ++q) { const float rs = __builtin_amdgcn_rsqf(wave_sum(s[q]) * (1.f / DM) + NORM_EPS);
	v_mul_f32_e32 v198, v57, v57
	v_mul_f32_e32 v199, v59, v59
	v_add_f32_e32 v195, v206, v207
	v_fmac_f32_e32 v191, v64, v64
	v_fmac_f32_e32 v192, v66, v66
	v_add_f32_e32 v179, v179, v194
	v_add_f32_e32 v180, v180, v193
	v_add_f32_e32 v190, v204, v205
	s_waitcnt vmcnt(1)
	v_mul_f32_e32 v200, v53, v53
	v_mul_f32_e32 v204, v55, v55
	v_fmac_f32_e32 v198, v56, v56
	v_fmac_f32_e32 v199, v58, v58
	v_add_f32_e32 v181, v191, v192
	v_add_f32_e32 v179, v179, v182
	v_add_f32_e32 v180, v180, v195
	s_waitcnt vmcnt(0)
	v_mul_f32_e32 v205, v49, v49
	v_mul_f32_e32 v208, v51, v51
	v_fmac_f32_e32 v200, v52, v52
	v_fmac_f32_e32 v204, v54, v54
	v_add_f32_e32 v183, v198, v199
	v_add_f32_e32 v179, v179, v188
	v_add_f32_e32 v180, v180, v181
	v_fmac_f32_e32 v205, v48, v48
	v_fmac_f32_e32 v208, v50, v50
	v_add_f32_e32 v191, v200, v204
	v_add_f32_e32 v179, v179, v189
	v_add_f32_e32 v180, v180, v183
	v_add_f32_e32 v192, v205, v208
	v_add_f32_e32 v179, v179, v190
	s_waitcnt lgkmcnt(0)
	v_add_f32_e32 v177, v177, v196
	v_add_f32_e32 v180, v180, v191
	v_add_f32_e32 v178, v178, v186
	ds_bpermute_b32 v181, v170, v179
	ds_bpermute_b32 v183, v171, v177
	v_add_f32_e32 v180, v180, v192
	v_add_f32_e32 v178, v178, v187
	ds_bpermute_b32 v186, v170, v180
	ds_bpermute_b32 v182, v170, v178
	s_waitcnt lgkmcnt(3)
	v_add_f32_e32 v179, v179, v181
	s_waitcnt lgkmcnt(2)
	v_add_f32_e32 v177, v177, v183
	ds_bpermute_b32 v181, v171, v179
	ds_bpermute_b32 v183, v172, v177
	s_waitcnt lgkmcnt(3)
	v_add_f32_e32 v180, v180, v186
	s_waitcnt lgkmcnt(2)
	v_add_f32_e32 v178, v178, v182
	ds_bpermute_b32 v186, v171, v180
	ds_bpermute_b32 v182, v171, v178
	s_waitcnt lgkmcnt(3)
	v_add_f32_e32 v179, v179, v181
	s_waitcnt lgkmcnt(2)
	v_add_f32_e32 v177, v177, v183
	ds_bpermute_b32 v181, v172, v179
	ds_bpermute_b32 v183, v173, v177
	s_waitcnt lgkmcnt(3)
	v_add_f32_e32 v180, v180, v186
	s_waitcnt lgkmcnt(2)
	v_add_f32_e32 v178, v178, v182
	ds_bpermute_b32 v186, v172, v180
	ds_bpermute_b32 v182, v172, v178
	s_waitcnt lgkmcnt(3)
	v_add_f32_e32 v179, v179, v181
	s_waitcnt lgkmcnt(2)
	v_add_f32_e32 v177, v177, v183
	ds_bpermute_b32 v181, v173, v179
	ds_bpermute_b32 v183, v174, v177
	s_waitcnt lgkmcnt(3)
	v_add_f32_e32 v180, v180, v186
	s_waitcnt lgkmcnt(2)
	v_add_f32_e32 v178, v178, v182
	ds_bpermute_b32 v186, v173, v180
	ds_bpermute_b32 v182, v173, v178
	s_waitcnt lgkmcnt(3)
	v_add_f32_e32 v179, v179, v181
	s_waitcnt lgkmcnt(2)
	v_add_f32_e32 v177, v177, v183
	ds_bpermute_b32 v181, v174, v179
	ds_bpermute_b32 v183, v175, v177
	s_waitcnt lgkmcnt(3)
	v_add_f32_e32 v180, v180, v186
	s_waitcnt lgkmcnt(2)
	v_add_f32_e32 v178, v178, v182
	ds_bpermute_b32 v186, v174, v180
	ds_bpermute_b32 v182, v174, v178
	s_waitcnt lgkmcnt(3)
	v_add_f32_e32 v179, v179, v181
	s_waitcnt lgkmcnt(2)
	v_add_f32_e32 v177, v177, v183
	ds_bpermute_b32 v181, v175, v179
	v_fmamk_f32 v177, v177, 0x3a000000, v176
	s_waitcnt lgkmcnt(2)
	v_add_f32_e32 v180, v180, v186
	s_waitcnt lgkmcnt(1)
	v_add_f32_e32 v178, v178, v182
	v_rsq_f32_e32 v177, v177
	ds_bpermute_b32 v183, v175, v180
	ds_bpermute_b32 v182, v175, v178
	s_waitcnt lgkmcnt(2)
	v_add_f32_e32 v179, v179, v181
	v_mul_f32_e32 v44, v177, v44
	v_mul_f32_e32 v45, v177, v45
	v_mul_f32_e32 v46, v177, v46
	v_mul_f32_e32 v47, v177, v47
	v_mul_f32_e32 v32, v177, v32
	v_mul_f32_e32 v33, v177, v33
	v_mul_f32_e32 v40, v177, v40
	v_mul_f32_e32 v41, v177, v41
	v_mul_f32_e32 v42, v177, v42
	v_mul_f32_e32 v43, v177, v43
	v_mul_f32_e32 v36, v177, v36
	v_mul_f32_e32 v37, v177, v37
	v_mul_f32_e32 v38, v177, v38
	v_mul_f32_e32 v39, v177, v39
	v_mul_f32_e32 v34, v177, v34
	v_mul_f32_e32 v35, v177, v35
	v_mul_f32_e32 v156, v177, v156
	v_mul_f32_e32 v157, v177, v157
	v_mul_f32_e32 v158, v177, v158
	v_mul_f32_e32 v159, v177, v159
	v_mul_f32_e32 v152, v177, v152
	v_mul_f32_e32 v153, v177, v153
	v_mul_f32_e32 v154, v177, v154
	v_mul_f32_e32 v155, v177, v155
	v_mul_f32_e32 v148, v177, v148
	v_mul_f32_e32 v149, v177, v149
	v_mul_f32_e32 v150, v177, v150
	v_mul_f32_e32 v151, v177, v151
	v_mul_f32_e32 v144, v177, v144
	v_mul_f32_e32 v145, v177, v145
	v_mul_f32_e32 v146, v177, v146
	v_mul_f32_e32 v147, v177, v147
	v_fmamk_f32 v177, v179, 0x3a000000, v176
	s_waitcnt lgkmcnt(1)
	v_add_f32_e32 v179, v180, v183
	v_mul_f32_e32 v44, v28, v44
	v_mul_f32_e32 v45, v29, v45
	v_mul_f32_e32 v46, v30, v46
	v_mul_f32_e32 v47, v31, v47
	v_mul_f32_e32 v180, v16, v32
	v_mul_f32_e32 v181, v17, v33
	v_cvt_pk_bf16_f32 v32, v44, v45
	v_cvt_pk_bf16_f32 v33, v46, v47
	s_waitcnt lgkmcnt(0)
; __device__ __forceinline__ unsigned cvtpk2(float lo, float hi) { unsigned r; asm volatile("v_cvt_pk_bf16_f32 %0, %1, %2" : "=v"(r) : "v"(lo), "v"(hi)); return r; }
; __global__ void __launch_bounds__(NWAVES * 64, 2) hybrid_fwd(Args args) {
;     ...
;             for (int q = 0; q < 4; ++q) { const float rs = __builtin_amdgcn_rsqf(wave_sum(s[q]) * (1.f / DM) + NORM_EPS);
;                 v2u* o8 = (v2u*)(HB + (size_t)(m0 + q) * DM) + lane;
; #pragma unroll
;                 for (int j = 0; j < 8; ++j) { const f32x4 w = wmix[j]; v2u o; o.x = cvtpk2(v[q][j].x * rs * w.x, v[q][j].y * rs * w.y); o.y = cvtpk2(v[q][j].z * rs * w.z, v[q][j].w * rs * w.w); o8[64 * j] = o; } }
	v_add_f32_e32 v178, v178, v182
	v_mul_f32_e32 v40, v24, v40
	v_mul_f32_e32 v41, v25, v41
	v_mul_f32_e32 v42, v26, v42
	v_mul_f32_e32 v43, v27, v43
	global_store_dwordx2 v[160:161], v[32:33], off
	v_cvt_pk_bf16_f32 v32, v40, v41
	v_cvt_pk_bf16_f32 v33, v42, v43
	v_fmamk_f32 v178, v178, 0x3a000000, v176
	v_mul_f32_e32 v36, v20, v36
	v_mul_f32_e32 v37, v21, v37
	v_mul_f32_e32 v38, v22, v38
	v_mul_f32_e32 v39, v23, v39
	global_store_dwordx2 v[160:161], v[32:33], off offset:512
	v_cvt_pk_bf16_f32 v32, v36, v37
	v_cvt_pk_bf16_f32 v33, v38, v39
	v_rsq_f32_e32 v178, v178
	v_mul_f32_e32 v34, v18, v34
	v_mul_f32_e32 v35, v19, v35
	global_store_dwordx2 v[160:161], v[32:33], off offset:1024
	v_cvt_pk_bf16_f32 v32, v180, v181
	v_cvt_pk_bf16_f32 v33, v34, v35
	v_mul_f32_e32 v156, v12, v156
	v_mul_f32_e32 v157, v13, v157
	v_mul_f32_e32 v158, v14, v158
	v_mul_f32_e32 v159, v15, v159
	global_store_dwordx2 v[160:161], v[32:33], off offset:1536
	v_cvt_pk_bf16_f32 v32, v156, v157
	v_cvt_pk_bf16_f32 v33, v158, v159
	v_mul_f32_e32 v152, v8, v152
	v_mul_f32_e32 v153, v9, v153
	v_mul_f32_e32 v154, v10, v154
	v_mul_f32_e32 v155, v11, v155
	global_store_dwordx2 v[160:161], v[32:33], off offset:2048
	v_cvt_pk_bf16_f32 v32, v152, v153
	v_cvt_pk_bf16_f32 v33, v154, v155
	v_mul_f32_e32 v148, v4, v148
	v_mul_f32_e32 v149, v5, v149
	v_mul_f32_e32 v150, v6, v150
	v_mul_f32_e32 v151, v7, v151
	global_store_dwordx2 v[160:161], v[32:33], off offset:2560
	v_cvt_pk_bf16_f32 v32, v148, v149
	v_cvt_pk_bf16_f32 v33, v150, v151
	v_mul_f32_e32 v144, v0, v144
	v_mul_f32_e32 v145, v1, v145
	v_mul_f32_e32 v146, v2, v146
	v_mul_f32_e32 v147, v3, v147
	v_mul_f32_e32 v44, v178, v140
	v_mul_f32_e32 v45, v178, v141
	v_mul_f32_e32 v46, v178, v142
	v_mul_f32_e32 v47, v178, v143
	global_store_dwordx2 v[160:161], v[32:33], off offset:3072
	v_cvt_pk_bf16_f32 v32, v144, v145
	v_cvt_pk_bf16_f32 v33, v146, v147
	v_mul_f32_e32 v136, v178, v136
	v_mul_f32_e32 v137, v178, v137
	v_mul_f32_e32 v138, v178, v138
	v_mul_f32_e32 v139, v178, v139
	v_mul_f32_e32 v36, v28, v44
	v_mul_f32_e32 v37, v29, v45
	v_mul_f32_e32 v38, v30, v46
	v_mul_f32_e32 v39, v31, v47
	global_store_dwordx2 v[160:161], v[32:33], off offset:3584
	v_cvt_pk_bf16_f32 v32, v36, v37
	v_cvt_pk_bf16_f32 v33, v38, v39
	v_mul_f32_e32 v132, v178, v132
	v_mul_f32_e32 v133, v178, v133
	v_mul_f32_e32 v134, v178, v134
	v_mul_f32_e32 v135, v178, v135
	v_mul_f32_e32 v40, v24, v136
	v_mul_f32_e32 v41, v25, v137
	v_mul_f32_e32 v42, v26, v138
	v_mul_f32_e32 v43, v27, v139
	global_store_dwordx2 v[166:167], v[32:33], off offset:-4096
	v_cvt_pk_bf16_f32 v32, v40, v41
	v_cvt_pk_bf16_f32 v33, v42, v43
	v_mul_f32_e32 v124, v178, v124
	v_mul_f32_e32 v125, v178, v125
	v_mul_f32_e32 v126, v178, v126
	v_mul_f32_e32 v127, v178, v127
	v_mul_f32_e32 v44, v20, v132
	v_mul_f32_e32 v45, v21, v133
	v_mul_f32_e32 v46, v22, v134
	v_mul_f32_e32 v47, v23, v135
	global_store_dwordx2 v[168:169], v[32:33], off offset:512
	v_cvt_pk_bf16_f32 v32, v44, v45
	v_cvt_pk_bf16_f32 v33, v46, v47
	v_rsq_f32_e32 v177, v177
	v_mul_f32_e32 v128, v178, v128
	v_mul_f32_e32 v129, v178, v129
	v_mul_f32_e32 v130, v178, v130
	v_mul_f32_e32 v131, v178, v131
	v_mul_f32_e32 v124, v16, v124
	v_mul_f32_e32 v125, v17, v125
	v_mul_f32_e32 v126, v18, v126
	v_mul_f32_e32 v127, v19, v127
	global_store_dwordx2 v[168:169], v[32:33], off offset:1024
	v_cvt_pk_bf16_f32 v32, v124, v125
	v_cvt_pk_bf16_f32 v33, v126, v127
	v_mul_f32_e32 v120, v178, v120
	v_mul_f32_e32 v121, v178, v121
	v_mul_f32_e32 v122, v178, v122
	v_mul_f32_e32 v123, v178, v123
	v_mul_f32_e32 v128, v12, v128
	v_mul_f32_e32 v129, v13, v129
	v_mul_f32_e32 v130, v14, v130
	v_mul_f32_e32 v131, v15, v131
	global_store_dwordx2 v[168:169], v[32:33], off offset:1536
	v_cvt_pk_bf16_f32 v32, v128, v129
	v_cvt_pk_bf16_f32 v33, v130, v131
	v_mul_f32_e32 v116, v178, v116
	v_mul_f32_e32 v117, v178, v117
	v_mul_f32_e32 v118, v178, v118
	v_mul_f32_e32 v119, v178, v119
	v_mul_f32_e32 v120, v8, v120
	v_mul_f32_e32 v121, v9, v121
	v_mul_f32_e32 v122, v10, v122
	v_mul_f32_e32 v123, v11, v123
	global_store_dwordx2 v[168:169], v[32:33], off offset:2048
	v_cvt_pk_bf16_f32 v32, v120, v121
	v_cvt_pk_bf16_f32 v33, v122, v123
	v_mul_f32_e32 v112, v178, v112
	v_mul_f32_e32 v113, v178, v113
	v_mul_f32_e32 v114, v178, v114
	v_mul_f32_e32 v115, v178, v115
	v_mul_f32_e32 v116, v4, v116
	v_mul_f32_e32 v117, v5, v117
	v_mul_f32_e32 v118, v6, v118
	v_mul_f32_e32 v119, v7, v119
	global_store_dwordx2 v[168:169], v[32:33], off offset:2560
	v_cvt_pk_bf16_f32 v32, v116, v117
	v_cvt_pk_bf16_f32 v33, v118, v119
	v_mul_f32_e32 v112, v0, v112
	v_mul_f32_e32 v113, v1, v113
	v_mul_f32_e32 v114, v2, v114
	v_mul_f32_e32 v115, v3, v115
	v_mul_f32_e32 v108, v177, v108
	v_mul_f32_e32 v109, v177, v109
	v_mul_f32_e32 v110, v177, v110
	v_mul_f32_e32 v111, v177, v111
	global_store_dwordx2 v[168:169], v[32:33], off offset:3072
	v_cvt_pk_bf16_f32 v32, v112, v113
	v_cvt_pk_bf16_f32 v33, v114, v115
	v_mul_f32_e32 v104, v177, v104
	v_mul_f32_e32 v105, v177, v105
	v_mul_f32_e32 v106, v177, v106
	v_mul_f32_e32 v107, v177, v107
	v_mul_f32_e32 v34, v28, v108
	v_mul_f32_e32 v35, v29, v109
	v_mul_f32_e32 v108, v30, v110
	v_mul_f32_e32 v109, v31, v111
	global_store_dwordx2 v[168:169], v[32:33], off offset:3584
	v_cvt_pk_bf16_f32 v32, v34, v35
	v_cvt_pk_bf16_f32 v33, v108, v109
	v_mul_f32_e32 v100, v177, v100
	v_mul_f32_e32 v101, v177, v101
	v_mul_f32_e32 v102, v177, v102
	v_mul_f32_e32 v103, v177, v103
; __device__ __forceinline__ unsigned cvtpk2(float lo, float hi) { unsigned r; asm volatile("v_cvt_pk_bf16_f32 %0, %1, %2" : "=v"(r) : "v"(lo), "v"(hi)); return r; }
; __global__ void __launch_bounds__(NWAVES * 64, 2) hybrid_fwd(Args args) {
;     ...
;             for (int q = 0; q < 4; ++q) { const float rs = __builtin_amdgcn_rsqf(wave_sum(s[q]) * (1.f / DM) + NORM_EPS);
;                 v2u* o8 = (v2u*)(HB + (size_t)(m0 + q) * DM) + lane;
; #pragma unroll
;                 for (int j = 0; j < 8; ++j) { const f32x4 w = wmix[j]; v2u o; o.x = cvtpk2(v[q][j].x * rs * w.x, v[q][j].y * rs * w.y); o.y = cvtpk2(v[q][j].z * rs * w.z, v[q][j].w * rs * w.w); o8[64 * j] = o; } }
;         }
	v_mul_f32_e32 v104, v24, v104
	v_mul_f32_e32 v105, v25, v105
	v_mul_f32_e32 v106, v26, v106
	v_mul_f32_e32 v107, v27, v107
	global_store_dwordx2 v[166:167], v[32:33], off
	v_cvt_pk_bf16_f32 v32, v104, v105
	v_cvt_pk_bf16_f32 v33, v106, v107
	v_fmamk_f32 v179, v179, 0x3a000000, v176
	v_mul_f32_e32 v96, v177, v96
	v_mul_f32_e32 v97, v177, v97
	v_mul_f32_e32 v98, v177, v98
	v_mul_f32_e32 v99, v177, v99
	v_mul_f32_e32 v100, v20, v100
	v_mul_f32_e32 v101, v21, v101
	v_mul_f32_e32 v102, v22, v102
	v_mul_f32_e32 v103, v23, v103
	global_store_dwordx2 v[166:167], v[32:33], off offset:512
	v_cvt_pk_bf16_f32 v32, v100, v101
	v_cvt_pk_bf16_f32 v33, v102, v103
	v_rsq_f32_e32 v140, v179
	v_mul_f32_e32 v92, v177, v92
	v_mul_f32_e32 v93, v177, v93
	v_mul_f32_e32 v94, v177, v94
	v_mul_f32_e32 v95, v177, v95
	v_mul_f32_e32 v96, v16, v96
	v_mul_f32_e32 v97, v17, v97
	v_mul_f32_e32 v98, v18, v98
	v_mul_f32_e32 v99, v19, v99
	global_store_dwordx2 v[166:167], v[32:33], off offset:1024
	v_cvt_pk_bf16_f32 v32, v96, v97
	v_cvt_pk_bf16_f32 v33, v98, v99
	v_mul_f32_e32 v88, v177, v88
	v_mul_f32_e32 v89, v177, v89
	v_mul_f32_e32 v90, v177, v90
	v_mul_f32_e32 v91, v177, v91
	v_mul_f32_e32 v92, v12, v92
	v_mul_f32_e32 v93, v13, v93
	v_mul_f32_e32 v94, v14, v94
	v_mul_f32_e32 v95, v15, v95
	global_store_dwordx2 v[166:167], v[32:33], off offset:1536
	v_cvt_pk_bf16_f32 v32, v92, v93
	v_cvt_pk_bf16_f32 v33, v94, v95
	v_mul_f32_e32 v84, v177, v84
	v_mul_f32_e32 v85, v177, v85
	v_mul_f32_e32 v86, v177, v86
	v_mul_f32_e32 v87, v177, v87
	v_mul_f32_e32 v88, v8, v88
	v_mul_f32_e32 v89, v9, v89
	v_mul_f32_e32 v90, v10, v90
	v_mul_f32_e32 v91, v11, v91
	global_store_dwordx2 v[166:167], v[32:33], off offset:2048
	v_cvt_pk_bf16_f32 v32, v88, v89
	v_cvt_pk_bf16_f32 v33, v90, v91
	v_mul_f32_e32 v80, v177, v80
	v_mul_f32_e32 v81, v177, v81
	v_mul_f32_e32 v82, v177, v82
	v_mul_f32_e32 v83, v177, v83
	v_mul_f32_e32 v84, v4, v84
	v_mul_f32_e32 v85, v5, v85
	v_mul_f32_e32 v86, v6, v86
	v_mul_f32_e32 v87, v7, v87
	global_store_dwordx2 v[166:167], v[32:33], off offset:2560
	v_cvt_pk_bf16_f32 v32, v84, v85
	v_cvt_pk_bf16_f32 v33, v86, v87
	v_mul_f32_e32 v80, v0, v80
	v_mul_f32_e32 v81, v1, v81
	v_mul_f32_e32 v82, v2, v82
	v_mul_f32_e32 v83, v3, v83
	v_mul_f32_e32 v76, v140, v76
	v_mul_f32_e32 v77, v140, v77
	v_mul_f32_e32 v78, v140, v78
	v_mul_f32_e32 v79, v140, v79
	global_store_dwordx2 v[166:167], v[32:33], off offset:3072
	v_cvt_pk_bf16_f32 v32, v80, v81
	v_cvt_pk_bf16_f32 v33, v82, v83
	v_mul_f32_e32 v72, v140, v72
	v_mul_f32_e32 v73, v140, v73
	v_mul_f32_e32 v74, v140, v74
	v_mul_f32_e32 v75, v140, v75
	v_mul_f32_e32 v76, v28, v76
	v_mul_f32_e32 v77, v29, v77
	v_mul_f32_e32 v78, v30, v78
	v_mul_f32_e32 v79, v31, v79
	global_store_dwordx2 v[166:167], v[32:33], off offset:3584
	v_cvt_pk_bf16_f32 v32, v76, v77
	v_cvt_pk_bf16_f32 v33, v78, v79
	v_mul_f32_e32 v68, v140, v68
	v_mul_f32_e32 v69, v140, v69
	v_mul_f32_e32 v70, v140, v70
	v_mul_f32_e32 v71, v140, v71
	v_mul_f32_e32 v72, v24, v72
	v_mul_f32_e32 v73, v25, v73
	v_mul_f32_e32 v74, v26, v74
	v_mul_f32_e32 v75, v27, v75
	global_store_dwordx2 v[164:165], v[32:33], off
	v_cvt_pk_bf16_f32 v32, v72, v73
	v_cvt_pk_bf16_f32 v33, v74, v75
	v_mul_f32_e32 v60, v140, v60
	v_mul_f32_e32 v61, v140, v61
	v_mul_f32_e32 v62, v140, v62
	v_mul_f32_e32 v63, v140, v63
	v_mul_f32_e32 v68, v20, v68
	v_mul_f32_e32 v69, v21, v69
	v_mul_f32_e32 v70, v22, v70
	v_mul_f32_e32 v71, v23, v71
	global_store_dwordx2 v[164:165], v[32:33], off offset:512
	v_cvt_pk_bf16_f32 v32, v68, v69
	v_cvt_pk_bf16_f32 v33, v70, v71
	v_mul_f32_e32 v64, v140, v64
	v_mul_f32_e32 v65, v140, v65
	v_mul_f32_e32 v66, v140, v66
	v_mul_f32_e32 v67, v140, v67
	v_mul_f32_e32 v60, v16, v60
	v_mul_f32_e32 v61, v17, v61
	v_mul_f32_e32 v62, v18, v62
	v_mul_f32_e32 v63, v19, v63
	global_store_dwordx2 v[164:165], v[32:33], off offset:1024
	v_cvt_pk_bf16_f32 v32, v60, v61
	v_cvt_pk_bf16_f32 v33, v62, v63
	v_mul_f32_e32 v56, v140, v56
	v_mul_f32_e32 v57, v140, v57
	v_mul_f32_e32 v58, v140, v58
	v_mul_f32_e32 v59, v140, v59
	v_mul_f32_e32 v64, v12, v64
	v_mul_f32_e32 v65, v13, v65
	v_mul_f32_e32 v66, v14, v66
	v_mul_f32_e32 v67, v15, v67
	global_store_dwordx2 v[164:165], v[32:33], off offset:1536
	v_cvt_pk_bf16_f32 v32, v64, v65
	v_cvt_pk_bf16_f32 v33, v66, v67
	v_mul_f32_e32 v52, v140, v52
	v_mul_f32_e32 v53, v140, v53
	v_mul_f32_e32 v54, v140, v54
	v_mul_f32_e32 v55, v140, v55
	v_mul_f32_e32 v56, v8, v56
	v_mul_f32_e32 v57, v9, v57
	v_mul_f32_e32 v58, v10, v58
	v_mul_f32_e32 v59, v11, v59
	global_store_dwordx2 v[164:165], v[32:33], off offset:2048
	v_cvt_pk_bf16_f32 v32, v56, v57
	v_cvt_pk_bf16_f32 v33, v58, v59
	v_lshl_add_u64 v[162:163], v[162:163], 0, s[16:17]
	v_mul_f32_e32 v48, v140, v48
	v_mul_f32_e32 v49, v140, v49
	v_mul_f32_e32 v50, v140, v50
	v_mul_f32_e32 v51, v140, v51
	v_mul_f32_e32 v52, v4, v52
	v_mul_f32_e32 v53, v5, v53
	v_mul_f32_e32 v54, v6, v54
	v_mul_f32_e32 v55, v7, v55
	v_lshl_add_u64 v[160:161], v[160:161], 0, s[14:15]
	global_store_dwordx2 v[164:165], v[32:33], off offset:2560
	v_cvt_pk_bf16_f32 v32, v52, v53
	v_cvt_pk_bf16_f32 v33, v54, v55
	v_mul_f32_e32 v48, v0, v48
	v_mul_f32_e32 v49, v1, v49
	v_mul_f32_e32 v50, v2, v50
	v_mul_f32_e32 v51, v3, v51
	global_store_dwordx2 v[164:165], v[32:33], off offset:3072
	v_cvt_pk_bf16_f32 v32, v48, v49
	v_cvt_pk_bf16_f32 v33, v50, v51
	global_store_dwordx2 v[164:165], v[32:33], off offset:3584
	s_cbranch_scc1 .LBB0_25
